# non-temporal hint on the FFN hidden-activation stores (written once, read by the next phase), on top of mask+wait edits
# speedup vs baseline: 1.0034x; 1.0017x over previous
.LBB0_556:
	s_mov_b32 s17, s37
	v_mov_b32_e32 v144, v146
	s_mov_b32 s19, s4
	v_mov_b32_e32 v152, v147
	s_lshl_b32 s24, s53, 1
	s_ashr_i32 s25, s17, 1
	s_add_i32 s24, s25, s24
	s_ashr_i32 s25, s24, 31
	s_lshl_b64 s[24:25], s[24:25], 22
	s_add_u32 s24, s60, s24
	s_addc_u32 s25, s61, s25
	s_lshl_b32 s8, s8, 8
	s_lshl_b32 s19, s19, 6
	s_add_i32 s19, s19, s8
	v_add_u32_e32 v144, s19, v144
	v_ashrrev_i32_e32 v145, 31, v144
	v_lshlrev_b64 v[144:145], 7, v[144:145]
	s_lshl_b32 s8, s17, 6
	v_lshl_add_u64 v[144:145], s[24:25], 0, v[144:145]
	s_and_b32 s8, s8, 64
	v_lshlrev_b32_e32 v152, 3, v152
	v_lshl_add_u64 v[144:145], v[144:145], 0, s[8:9]
	v_ashrrev_i32_e32 v153, 31, v152
	v_lshl_add_u64 v[144:145], v[152:153], 1, v[144:145]
	v_pk_mul_f32 v[152:153], v[126:127], s[14:15] op_sel_hi:[1,0]
	v_pk_mul_f32 v[154:155], v[124:125], s[14:15] op_sel_hi:[1,0]
	v_pk_mul_f32 v[156:157], v[122:123], s[14:15] op_sel_hi:[1,0]
	v_pk_mul_f32 v[158:159], v[120:121], s[14:15] op_sel_hi:[1,0]
	v_exp_f32_e32 v154, v154
	v_exp_f32_e32 v158, v158
	v_exp_f32_e32 v155, v155
	v_exp_f32_e32 v152, v152
	v_exp_f32_e32 v153, v153
	v_exp_f32_e32 v156, v156
	v_exp_f32_e32 v157, v157
	v_exp_f32_e32 v159, v159
	v_pk_add_f32 v[152:153], v[152:153], 1.0 op_sel_hi:[1,0]
	v_pk_add_f32 v[154:155], v[154:155], 1.0 op_sel_hi:[1,0]
	v_pk_add_f32 v[156:157], v[156:157], 1.0 op_sel_hi:[1,0]
	v_pk_add_f32 v[158:159], v[158:159], 1.0 op_sel_hi:[1,0]
	v_rcp_f32_e32 v154, v154
	v_rcp_f32_e32 v158, v158
	v_rcp_f32_e32 v155, v155
	v_rcp_f32_e32 v159, v159
	v_rcp_f32_e32 v152, v152
	v_rcp_f32_e32 v156, v156
	v_rcp_f32_e32 v153, v153
	v_rcp_f32_e32 v157, v157
	v_pk_mul_f32 v[118:119], v[126:127], v[118:119]
	v_pk_mul_f32 v[116:117], v[124:125], v[116:117]
	v_pk_mul_f32 v[114:115], v[122:123], v[114:115]
	v_pk_mul_f32 v[112:113], v[120:121], v[112:113]
	v_pk_mul_f32 v[118:119], v[152:153], v[118:119]
	v_pk_mul_f32 v[116:117], v[154:155], v[116:117]
	v_pk_mul_f32 v[120:121], v[156:157], v[114:115]
	v_pk_mul_f32 v[114:115], v[158:159], v[112:113]
	v_cvt_pk_bf16_f32 v112, v116, v117
	v_cvt_pk_bf16_f32 v113, v118, v119
	v_pk_mul_f32 v[116:117], v[106:107], s[14:15] op_sel_hi:[1,0]
	v_cvt_pk_bf16_f32 v114, v114, v115
	v_cvt_pk_bf16_f32 v115, v120, v121
	v_pk_mul_f32 v[118:119], v[104:105], s[14:15] op_sel_hi:[1,0]
	global_store_dwordx4 v[144:145], v[112:115], off nt
	v_exp_f32_e32 v118, v118
	v_exp_f32_e32 v116, v116
	v_pk_mul_f32 v[112:113], v[110:111], s[14:15] op_sel_hi:[1,0]
	v_pk_mul_f32 v[114:115], v[108:109], s[14:15] op_sel_hi:[1,0]
	v_exp_f32_e32 v117, v117
	v_exp_f32_e32 v119, v119
	v_exp_f32_e32 v114, v114
	v_exp_f32_e32 v115, v115
	v_exp_f32_e32 v112, v112
	v_exp_f32_e32 v113, v113
	v_pk_add_f32 v[116:117], v[116:117], 1.0 op_sel_hi:[1,0]
	v_pk_add_f32 v[118:119], v[118:119], 1.0 op_sel_hi:[1,0]
	v_pk_add_f32 v[114:115], v[114:115], 1.0 op_sel_hi:[1,0]
	v_pk_add_f32 v[112:113], v[112:113], 1.0 op_sel_hi:[1,0]
	v_rcp_f32_e32 v118, v118
	v_rcp_f32_e32 v119, v119
	v_rcp_f32_e32 v116, v116
	v_rcp_f32_e32 v117, v117
	v_rcp_f32_e32 v114, v114
	v_rcp_f32_e32 v115, v115
	v_rcp_f32_e32 v112, v112
	v_rcp_f32_e32 v113, v113
	v_pk_mul_f32 v[98:99], v[106:107], v[98:99]
	v_pk_mul_f32 v[96:97], v[104:105], v[96:97]
	v_pk_mul_f32 v[102:103], v[110:111], v[102:103]
	v_pk_mul_f32 v[100:101], v[108:109], v[100:101]
	v_pk_mul_f32 v[104:105], v[116:117], v[98:99]
	v_pk_mul_f32 v[98:99], v[118:119], v[96:97]
	v_pk_mul_f32 v[102:103], v[112:113], v[102:103]
	v_pk_mul_f32 v[100:101], v[114:115], v[100:101]
	v_pk_mul_f32 v[84:85], v[92:93], v[84:85]
	v_cvt_pk_bf16_f32 v96, v100, v101
	v_cvt_pk_bf16_f32 v97, v102, v103
	v_cvt_pk_bf16_f32 v98, v98, v99
	v_cvt_pk_bf16_f32 v99, v104, v105
	global_store_dwordx4 v[144:145], v[96:99], off offset:2048 nt
	v_pk_mul_f32 v[100:101], v[90:91], s[14:15] op_sel_hi:[1,0]
	v_pk_mul_f32 v[102:103], v[88:89], s[14:15] op_sel_hi:[1,0]
	v_pk_mul_f32 v[98:99], v[92:93], s[14:15] op_sel_hi:[1,0]
	v_pk_mul_f32 v[96:97], v[94:95], s[14:15] op_sel_hi:[1,0]
	v_exp_f32_e32 v98, v98
	v_exp_f32_e32 v99, v99
	v_exp_f32_e32 v102, v102
	v_exp_f32_e32 v96, v96
	v_exp_f32_e32 v97, v97
	v_exp_f32_e32 v100, v100
	v_exp_f32_e32 v101, v101
	v_exp_f32_e32 v103, v103
	v_pk_add_f32 v[98:99], v[98:99], 1.0 op_sel_hi:[1,0]
	v_pk_add_f32 v[96:97], v[96:97], 1.0 op_sel_hi:[1,0]
	v_pk_add_f32 v[100:101], v[100:101], 1.0 op_sel_hi:[1,0]
	v_pk_add_f32 v[102:103], v[102:103], 1.0 op_sel_hi:[1,0]
	v_rcp_f32_e32 v98, v98
	v_rcp_f32_e32 v99, v99
	v_rcp_f32_e32 v102, v102
	v_rcp_f32_e32 v103, v103
	v_rcp_f32_e32 v96, v96
	v_rcp_f32_e32 v100, v100
	v_rcp_f32_e32 v97, v97
	v_rcp_f32_e32 v101, v101
	v_pk_mul_f32 v[86:87], v[94:95], v[86:87]
	v_pk_mul_f32 v[84:85], v[98:99], v[84:85]
	v_pk_mul_f32 v[82:83], v[90:91], v[82:83]
	v_pk_mul_f32 v[80:81], v[88:89], v[80:81]
	v_pk_mul_f32 v[86:87], v[96:97], v[86:87]
	v_pk_mul_f32 v[88:89], v[100:101], v[82:83]
	v_pk_mul_f32 v[82:83], v[102:103], v[80:81]
	v_cvt_pk_bf16_f32 v80, v84, v85
	v_add_co_u32_e32 v84, vcc, s44, v144
	v_cvt_pk_bf16_f32 v81, v86, v87
	v_cvt_pk_bf16_f32 v82, v82, v83
	v_cvt_pk_bf16_f32 v83, v88, v89
	v_pk_mul_f32 v[86:87], v[74:75], s[14:15] op_sel_hi:[1,0]
	s_nop 0
	v_addc_co_u32_e32 v85, vcc, 0, v145, vcc
	v_pk_mul_f32 v[88:89], v[72:73], s[14:15] op_sel_hi:[1,0]
	global_store_dwordx4 v[84:85], v[80:83], off nt
	v_exp_f32_e32 v88, v88
	v_exp_f32_e32 v86, v86
	v_pk_mul_f32 v[80:81], v[78:79], s[14:15] op_sel_hi:[1,0]
	v_pk_mul_f32 v[82:83], v[76:77], s[14:15] op_sel_hi:[1,0]
	v_exp_f32_e32 v87, v87
	v_exp_f32_e32 v89, v89
	v_exp_f32_e32 v82, v82
	v_exp_f32_e32 v83, v83
	v_exp_f32_e32 v80, v80
	v_exp_f32_e32 v81, v81
	v_pk_add_f32 v[86:87], v[86:87], 1.0 op_sel_hi:[1,0]
	v_pk_add_f32 v[88:89], v[88:89], 1.0 op_sel_hi:[1,0]
	v_pk_add_f32 v[82:83], v[82:83], 1.0 op_sel_hi:[1,0]
	v_pk_add_f32 v[80:81], v[80:81], 1.0 op_sel_hi:[1,0]
	v_rcp_f32_e32 v88, v88
	v_rcp_f32_e32 v89, v89
	v_rcp_f32_e32 v86, v86
	v_rcp_f32_e32 v87, v87
	v_rcp_f32_e32 v82, v82
	v_rcp_f32_e32 v83, v83
	v_rcp_f32_e32 v80, v80
	v_rcp_f32_e32 v81, v81
	v_pk_mul_f32 v[66:67], v[74:75], v[66:67]
	v_pk_mul_f32 v[64:65], v[72:73], v[64:65]
	v_pk_mul_f32 v[70:71], v[78:79], v[70:71]
	v_pk_mul_f32 v[68:69], v[76:77], v[68:69]
	v_pk_mul_f32 v[72:73], v[86:87], v[66:67]
	v_pk_mul_f32 v[66:67], v[88:89], v[64:65]
	v_pk_mul_f32 v[70:71], v[80:81], v[70:71]
	v_pk_mul_f32 v[68:69], v[82:83], v[68:69]
	v_pk_mul_f32 v[52:53], v[60:61], v[52:53]
	v_cvt_pk_bf16_f32 v64, v68, v69
	v_cvt_pk_bf16_f32 v65, v70, v71
	v_cvt_pk_bf16_f32 v66, v66, v67
	v_cvt_pk_bf16_f32 v67, v72, v73
	global_store_dwordx4 v[84:85], v[64:67], off offset:2048 nt
	v_pk_mul_f32 v[68:69], v[58:59], s[14:15] op_sel_hi:[1,0]
	v_pk_mul_f32 v[70:71], v[56:57], s[14:15] op_sel_hi:[1,0]
	v_pk_mul_f32 v[66:67], v[60:61], s[14:15] op_sel_hi:[1,0]
	v_pk_mul_f32 v[64:65], v[62:63], s[14:15] op_sel_hi:[1,0]
	v_exp_f32_e32 v66, v66
	v_exp_f32_e32 v67, v67
	v_exp_f32_e32 v70, v70
	v_exp_f32_e32 v68, v68
	v_exp_f32_e32 v69, v69
	v_exp_f32_e32 v71, v71
	v_exp_f32_e32 v64, v64
	v_exp_f32_e32 v65, v65
	v_pk_add_f32 v[66:67], v[66:67], 1.0 op_sel_hi:[1,0]
	v_pk_add_f32 v[68:69], v[68:69], 1.0 op_sel_hi:[1,0]
	v_pk_add_f32 v[70:71], v[70:71], 1.0 op_sel_hi:[1,0]
	v_rcp_f32_e32 v66, v66
	v_rcp_f32_e32 v67, v67
	v_pk_add_f32 v[64:65], v[64:65], 1.0 op_sel_hi:[1,0]
	v_rcp_f32_e32 v70, v70
	v_rcp_f32_e32 v71, v71
	v_rcp_f32_e32 v68, v68
	v_rcp_f32_e32 v69, v69
	v_rcp_f32_e32 v64, v64
	v_rcp_f32_e32 v65, v65
	v_pk_mul_f32 v[52:53], v[66:67], v[52:53]
	v_pk_mul_f32 v[50:51], v[58:59], v[50:51]
	v_pk_mul_f32 v[48:49], v[56:57], v[48:49]
	v_pk_mul_f32 v[54:55], v[62:63], v[54:55]
	v_pk_mul_f32 v[56:57], v[68:69], v[50:51]
	v_pk_mul_f32 v[50:51], v[70:71], v[48:49]
	v_cvt_pk_bf16_f32 v48, v52, v53
	v_add_co_u32_e32 v52, vcc, s36, v144
	v_pk_mul_f32 v[54:55], v[64:65], v[54:55]
	s_nop 0
	v_addc_co_u32_e32 v53, vcc, 0, v145, vcc
	v_cvt_pk_bf16_f32 v49, v54, v55
	v_add_co_u32_e32 v54, vcc, s45, v144
	v_cvt_pk_bf16_f32 v50, v50, v51
	v_cvt_pk_bf16_f32 v51, v56, v57
	v_pk_mul_f32 v[56:57], v[42:43], s[14:15] op_sel_hi:[1,0]
	s_nop 0
	v_addc_co_u32_e32 v55, vcc, 0, v145, vcc
	v_pk_mul_f32 v[58:59], v[40:41], s[14:15] op_sel_hi:[1,0]
	global_store_dwordx4 v[54:55], v[48:51], off offset:-4096 nt
	v_exp_f32_e32 v58, v58
	v_exp_f32_e32 v56, v56
	v_pk_mul_f32 v[48:49], v[46:47], s[14:15] op_sel_hi:[1,0]
	v_pk_mul_f32 v[50:51], v[44:45], s[14:15] op_sel_hi:[1,0]
	v_exp_f32_e32 v57, v57
	v_exp_f32_e32 v59, v59
	v_exp_f32_e32 v50, v50
	v_exp_f32_e32 v51, v51
	v_exp_f32_e32 v48, v48
	v_exp_f32_e32 v49, v49
	v_pk_add_f32 v[56:57], v[56:57], 1.0 op_sel_hi:[1,0]
	v_pk_add_f32 v[58:59], v[58:59], 1.0 op_sel_hi:[1,0]
	v_pk_add_f32 v[50:51], v[50:51], 1.0 op_sel_hi:[1,0]
	v_pk_add_f32 v[48:49], v[48:49], 1.0 op_sel_hi:[1,0]
	v_rcp_f32_e32 v58, v58
	v_rcp_f32_e32 v59, v59
	v_rcp_f32_e32 v56, v56
	v_rcp_f32_e32 v57, v57
	v_rcp_f32_e32 v50, v50
	v_rcp_f32_e32 v51, v51
	v_rcp_f32_e32 v48, v48
	v_rcp_f32_e32 v49, v49
	v_pk_mul_f32 v[34:35], v[42:43], v[34:35]
	v_pk_mul_f32 v[32:33], v[40:41], v[32:33]
	v_pk_mul_f32 v[38:39], v[46:47], v[38:39]
	v_pk_mul_f32 v[36:37], v[44:45], v[36:37]
	v_pk_mul_f32 v[40:41], v[56:57], v[34:35]
	v_pk_mul_f32 v[34:35], v[58:59], v[32:33]
	v_pk_mul_f32 v[38:39], v[48:49], v[38:39]
	v_pk_mul_f32 v[36:37], v[50:51], v[36:37]
	v_pk_mul_f32 v[22:23], v[30:31], v[22:23]
	v_cvt_pk_bf16_f32 v32, v36, v37
	v_cvt_pk_bf16_f32 v33, v38, v39
	v_cvt_pk_bf16_f32 v34, v34, v35
	v_cvt_pk_bf16_f32 v35, v40, v41
	global_store_dwordx4 v[52:53], v[32:35], off offset:2048 nt
	v_pk_mul_f32 v[36:37], v[26:27], s[14:15] op_sel_hi:[1,0]
	v_pk_mul_f32 v[38:39], v[24:25], s[14:15] op_sel_hi:[1,0]
	v_pk_mul_f32 v[32:33], v[30:31], s[14:15] op_sel_hi:[1,0]
	v_pk_mul_f32 v[34:35], v[28:29], s[14:15] op_sel_hi:[1,0]
	v_exp_f32_e32 v38, v38
	v_exp_f32_e32 v34, v34
	v_exp_f32_e32 v35, v35
	v_exp_f32_e32 v32, v32
	v_exp_f32_e32 v33, v33
	v_exp_f32_e32 v36, v36
	v_exp_f32_e32 v37, v37
	v_exp_f32_e32 v39, v39
	v_pk_add_f32 v[32:33], v[32:33], 1.0 op_sel_hi:[1,0]
	v_pk_add_f32 v[34:35], v[34:35], 1.0 op_sel_hi:[1,0]
	v_pk_add_f32 v[36:37], v[36:37], 1.0 op_sel_hi:[1,0]
	v_pk_add_f32 v[38:39], v[38:39], 1.0 op_sel_hi:[1,0]
	v_rcp_f32_e32 v34, v34
	v_rcp_f32_e32 v38, v38
	v_rcp_f32_e32 v35, v35
	v_rcp_f32_e32 v39, v39
	v_rcp_f32_e32 v32, v32
	v_rcp_f32_e32 v36, v36
	v_rcp_f32_e32 v33, v33
	v_rcp_f32_e32 v37, v37
	v_pk_mul_f32 v[20:21], v[28:29], v[20:21]
	v_pk_mul_f32 v[18:19], v[26:27], v[18:19]
	v_pk_mul_f32 v[16:17], v[24:25], v[16:17]
	v_pk_mul_f32 v[22:23], v[32:33], v[22:23]
	v_pk_mul_f32 v[20:21], v[34:35], v[20:21]
	v_pk_mul_f32 v[24:25], v[36:37], v[18:19]
	v_pk_mul_f32 v[18:19], v[38:39], v[16:17]
	v_cvt_pk_bf16_f32 v16, v20, v21
	v_cvt_pk_bf16_f32 v17, v22, v23
	v_pk_mul_f32 v[20:21], v[10:11], s[14:15] op_sel_hi:[1,0]
	v_cvt_pk_bf16_f32 v18, v18, v19
	v_cvt_pk_bf16_f32 v19, v24, v25
	v_pk_mul_f32 v[22:23], v[8:9], s[14:15] op_sel_hi:[1,0]
	global_store_dwordx4 v[54:55], v[16:19], off nt
	v_exp_f32_e32 v22, v22
	v_exp_f32_e32 v20, v20
	v_pk_mul_f32 v[16:17], v[14:15], s[14:15] op_sel_hi:[1,0]
	v_pk_mul_f32 v[18:19], v[12:13], s[14:15] op_sel_hi:[1,0]
	v_exp_f32_e32 v21, v21
	v_exp_f32_e32 v23, v23
	v_exp_f32_e32 v18, v18
	v_exp_f32_e32 v19, v19
	v_exp_f32_e32 v16, v16
	v_exp_f32_e32 v17, v17
	v_pk_add_f32 v[20:21], v[20:21], 1.0 op_sel_hi:[1,0]
	v_pk_add_f32 v[22:23], v[22:23], 1.0 op_sel_hi:[1,0]
	v_pk_add_f32 v[18:19], v[18:19], 1.0 op_sel_hi:[1,0]
	v_pk_add_f32 v[16:17], v[16:17], 1.0 op_sel_hi:[1,0]
	v_rcp_f32_e32 v22, v22
	v_rcp_f32_e32 v23, v23
	v_rcp_f32_e32 v20, v20
	v_rcp_f32_e32 v21, v21
	v_rcp_f32_e32 v18, v18
	v_rcp_f32_e32 v19, v19
	v_rcp_f32_e32 v16, v16
	v_rcp_f32_e32 v17, v17
	v_pk_mul_f32 v[2:3], v[10:11], v[2:3]
	v_pk_mul_f32 v[0:1], v[8:9], v[0:1]
	v_pk_mul_f32 v[6:7], v[14:15], v[6:7]
	v_pk_mul_f32 v[4:5], v[12:13], v[4:5]
	v_pk_mul_f32 v[8:9], v[20:21], v[2:3]
	v_pk_mul_f32 v[2:3], v[22:23], v[0:1]
	s_andn2_b64 vcc, exec, s[6:7]
	s_mov_b64 s[6:7], -1
	v_pk_mul_f32 v[6:7], v[16:17], v[6:7]
	v_pk_mul_f32 v[4:5], v[18:19], v[4:5]
	s_nop 0
	v_cvt_pk_bf16_f32 v0, v4, v5
	v_cvt_pk_bf16_f32 v1, v6, v7
	v_cvt_pk_bf16_f32 v2, v2, v3
	v_cvt_pk_bf16_f32 v3, v8, v9
	global_store_dwordx4 v[54:55], v[0:3], off offset:2048 nt
	s_cbranch_vccnz .LBB0_549
	s_andn2_b64 vcc, exec, s[10:11]
	s_cbranch_vccnz .LBB0_548
	s_barrier
	s_branch .LBB0_548

.LBB0_1631:
	v_mov_b32_e32 v152, v147
	s_mov_b32 s17, s38
	v_mov_b32_e32 v144, v146
	s_mov_b32 s19, s15
	s_lshl_b32 s24, s45, 1
	s_ashr_i32 s25, s17, 1
	s_add_i32 s24, s25, s24
	s_ashr_i32 s25, s24, 31
	s_lshl_b64 s[24:25], s[24:25], 22
	s_add_u32 s24, s60, s24
	s_addc_u32 s25, s61, s25
	s_lshl_b32 s8, s8, 8
	s_lshl_b32 s19, s19, 6
	s_add_i32 s19, s19, s8
	v_add_u32_e32 v144, s19, v144
	v_ashrrev_i32_e32 v145, 31, v144
	v_lshlrev_b64 v[144:145], 7, v[144:145]
	s_lshl_b32 s8, s17, 6
	v_lshl_add_u64 v[144:145], s[24:25], 0, v[144:145]
	s_and_b32 s8, s8, 64
	v_lshlrev_b32_e32 v152, 3, v152
	v_lshl_add_u64 v[144:145], v[144:145], 0, s[8:9]
	v_ashrrev_i32_e32 v153, 31, v152
	v_lshl_add_u64 v[144:145], v[152:153], 1, v[144:145]
	v_pk_mul_f32 v[152:153], v[126:127], s[14:15] op_sel_hi:[1,0]
	v_pk_mul_f32 v[154:155], v[124:125], s[14:15] op_sel_hi:[1,0]
	v_pk_mul_f32 v[156:157], v[122:123], s[14:15] op_sel_hi:[1,0]
	v_pk_mul_f32 v[158:159], v[120:121], s[14:15] op_sel_hi:[1,0]
	v_exp_f32_e32 v154, v154
	v_exp_f32_e32 v158, v158
	v_exp_f32_e32 v155, v155
	v_exp_f32_e32 v152, v152
	v_exp_f32_e32 v153, v153
	v_exp_f32_e32 v156, v156
	v_exp_f32_e32 v157, v157
	v_exp_f32_e32 v159, v159
	v_pk_add_f32 v[152:153], v[152:153], 1.0 op_sel_hi:[1,0]
	v_pk_add_f32 v[154:155], v[154:155], 1.0 op_sel_hi:[1,0]
	v_pk_add_f32 v[156:157], v[156:157], 1.0 op_sel_hi:[1,0]
	v_pk_add_f32 v[158:159], v[158:159], 1.0 op_sel_hi:[1,0]
	v_rcp_f32_e32 v154, v154
	v_rcp_f32_e32 v158, v158
	v_rcp_f32_e32 v155, v155
	v_rcp_f32_e32 v159, v159
	v_rcp_f32_e32 v152, v152
	v_rcp_f32_e32 v156, v156
	v_rcp_f32_e32 v153, v153
	v_rcp_f32_e32 v157, v157
	v_pk_mul_f32 v[118:119], v[126:127], v[118:119]
	v_pk_mul_f32 v[116:117], v[124:125], v[116:117]
	v_pk_mul_f32 v[114:115], v[122:123], v[114:115]
	v_pk_mul_f32 v[112:113], v[120:121], v[112:113]
	v_pk_mul_f32 v[118:119], v[152:153], v[118:119]
	v_pk_mul_f32 v[116:117], v[154:155], v[116:117]
	v_pk_mul_f32 v[120:121], v[156:157], v[114:115]
	v_pk_mul_f32 v[114:115], v[158:159], v[112:113]
	v_cvt_pk_bf16_f32 v112, v116, v117
	v_cvt_pk_bf16_f32 v113, v118, v119
	v_pk_mul_f32 v[116:117], v[106:107], s[14:15] op_sel_hi:[1,0]
	v_cvt_pk_bf16_f32 v114, v114, v115
	v_cvt_pk_bf16_f32 v115, v120, v121
	v_pk_mul_f32 v[118:119], v[104:105], s[14:15] op_sel_hi:[1,0]
	global_store_dwordx4 v[144:145], v[112:115], off nt
	v_exp_f32_e32 v118, v118
	v_exp_f32_e32 v116, v116
	v_pk_mul_f32 v[112:113], v[110:111], s[14:15] op_sel_hi:[1,0]
	v_pk_mul_f32 v[114:115], v[108:109], s[14:15] op_sel_hi:[1,0]
	v_exp_f32_e32 v117, v117
	v_exp_f32_e32 v119, v119
	v_exp_f32_e32 v114, v114
	v_exp_f32_e32 v115, v115
	v_exp_f32_e32 v112, v112
	v_exp_f32_e32 v113, v113
	v_pk_add_f32 v[116:117], v[116:117], 1.0 op_sel_hi:[1,0]
	v_pk_add_f32 v[118:119], v[118:119], 1.0 op_sel_hi:[1,0]
	v_pk_add_f32 v[114:115], v[114:115], 1.0 op_sel_hi:[1,0]
	v_pk_add_f32 v[112:113], v[112:113], 1.0 op_sel_hi:[1,0]
	v_rcp_f32_e32 v118, v118
	v_rcp_f32_e32 v119, v119
	v_rcp_f32_e32 v116, v116
	v_rcp_f32_e32 v117, v117
	v_rcp_f32_e32 v114, v114
	v_rcp_f32_e32 v115, v115
	v_rcp_f32_e32 v112, v112
	v_rcp_f32_e32 v113, v113
	v_pk_mul_f32 v[98:99], v[106:107], v[98:99]
	v_pk_mul_f32 v[96:97], v[104:105], v[96:97]
	v_pk_mul_f32 v[102:103], v[110:111], v[102:103]
	v_pk_mul_f32 v[100:101], v[108:109], v[100:101]
	v_pk_mul_f32 v[104:105], v[116:117], v[98:99]
	v_pk_mul_f32 v[98:99], v[118:119], v[96:97]
	v_pk_mul_f32 v[102:103], v[112:113], v[102:103]
	v_pk_mul_f32 v[100:101], v[114:115], v[100:101]
	v_pk_mul_f32 v[84:85], v[92:93], v[84:85]
	v_cvt_pk_bf16_f32 v96, v100, v101
	v_cvt_pk_bf16_f32 v97, v102, v103
	v_cvt_pk_bf16_f32 v98, v98, v99
	v_cvt_pk_bf16_f32 v99, v104, v105
	global_store_dwordx4 v[144:145], v[96:99], off offset:2048 nt
	v_pk_mul_f32 v[100:101], v[90:91], s[14:15] op_sel_hi:[1,0]
	v_pk_mul_f32 v[102:103], v[88:89], s[14:15] op_sel_hi:[1,0]
	v_pk_mul_f32 v[98:99], v[92:93], s[14:15] op_sel_hi:[1,0]
	v_pk_mul_f32 v[96:97], v[94:95], s[14:15] op_sel_hi:[1,0]
	v_exp_f32_e32 v98, v98
	v_exp_f32_e32 v99, v99
	v_exp_f32_e32 v102, v102
	v_exp_f32_e32 v96, v96
	v_exp_f32_e32 v97, v97
	v_exp_f32_e32 v100, v100
	v_exp_f32_e32 v101, v101
	v_exp_f32_e32 v103, v103
	v_pk_add_f32 v[98:99], v[98:99], 1.0 op_sel_hi:[1,0]
	v_pk_add_f32 v[96:97], v[96:97], 1.0 op_sel_hi:[1,0]
	v_pk_add_f32 v[100:101], v[100:101], 1.0 op_sel_hi:[1,0]
	v_pk_add_f32 v[102:103], v[102:103], 1.0 op_sel_hi:[1,0]
	v_rcp_f32_e32 v98, v98
	v_rcp_f32_e32 v99, v99
	v_rcp_f32_e32 v102, v102
	v_rcp_f32_e32 v103, v103
	v_rcp_f32_e32 v96, v96
	v_rcp_f32_e32 v100, v100
	v_rcp_f32_e32 v97, v97
	v_rcp_f32_e32 v101, v101
	v_pk_mul_f32 v[86:87], v[94:95], v[86:87]
	v_pk_mul_f32 v[84:85], v[98:99], v[84:85]
	v_pk_mul_f32 v[82:83], v[90:91], v[82:83]
	v_pk_mul_f32 v[80:81], v[88:89], v[80:81]
	s_movk_i32 s8, 0x1000
	v_pk_mul_f32 v[86:87], v[96:97], v[86:87]
	v_pk_mul_f32 v[88:89], v[100:101], v[82:83]
	v_pk_mul_f32 v[82:83], v[102:103], v[80:81]
	v_cvt_pk_bf16_f32 v80, v84, v85
	v_add_co_u32_e32 v84, vcc, s8, v144
	v_cvt_pk_bf16_f32 v81, v86, v87
	v_cvt_pk_bf16_f32 v82, v82, v83
	v_cvt_pk_bf16_f32 v83, v88, v89
	v_pk_mul_f32 v[86:87], v[74:75], s[14:15] op_sel_hi:[1,0]
	s_nop 0
	v_addc_co_u32_e32 v85, vcc, 0, v145, vcc
	v_pk_mul_f32 v[88:89], v[72:73], s[14:15] op_sel_hi:[1,0]
	global_store_dwordx4 v[84:85], v[80:83], off nt
	v_exp_f32_e32 v88, v88
	v_exp_f32_e32 v86, v86
	v_pk_mul_f32 v[80:81], v[78:79], s[14:15] op_sel_hi:[1,0]
	v_pk_mul_f32 v[82:83], v[76:77], s[14:15] op_sel_hi:[1,0]
	v_exp_f32_e32 v87, v87
	v_exp_f32_e32 v89, v89
	v_exp_f32_e32 v82, v82
	v_exp_f32_e32 v83, v83
	v_exp_f32_e32 v80, v80
	v_exp_f32_e32 v81, v81
	v_pk_add_f32 v[86:87], v[86:87], 1.0 op_sel_hi:[1,0]
	v_pk_add_f32 v[88:89], v[88:89], 1.0 op_sel_hi:[1,0]
	v_pk_add_f32 v[82:83], v[82:83], 1.0 op_sel_hi:[1,0]
	v_pk_add_f32 v[80:81], v[80:81], 1.0 op_sel_hi:[1,0]
	v_rcp_f32_e32 v88, v88
	v_rcp_f32_e32 v89, v89
	v_rcp_f32_e32 v86, v86
	v_rcp_f32_e32 v87, v87
	v_rcp_f32_e32 v82, v82
	v_rcp_f32_e32 v83, v83
	v_rcp_f32_e32 v80, v80
	v_rcp_f32_e32 v81, v81
	v_pk_mul_f32 v[66:67], v[74:75], v[66:67]
	v_pk_mul_f32 v[64:65], v[72:73], v[64:65]
	v_pk_mul_f32 v[70:71], v[78:79], v[70:71]
	v_pk_mul_f32 v[68:69], v[76:77], v[68:69]
	v_pk_mul_f32 v[72:73], v[86:87], v[66:67]
	v_pk_mul_f32 v[66:67], v[88:89], v[64:65]
	v_pk_mul_f32 v[70:71], v[80:81], v[70:71]
	v_pk_mul_f32 v[68:69], v[82:83], v[68:69]
	v_pk_mul_f32 v[52:53], v[60:61], v[52:53]
	v_cvt_pk_bf16_f32 v64, v68, v69
	v_cvt_pk_bf16_f32 v65, v70, v71
	v_cvt_pk_bf16_f32 v66, v66, v67
	v_cvt_pk_bf16_f32 v67, v72, v73
	global_store_dwordx4 v[84:85], v[64:67], off offset:2048 nt
	v_pk_mul_f32 v[68:69], v[58:59], s[14:15] op_sel_hi:[1,0]
	v_pk_mul_f32 v[70:71], v[56:57], s[14:15] op_sel_hi:[1,0]
	v_pk_mul_f32 v[66:67], v[60:61], s[14:15] op_sel_hi:[1,0]
	v_pk_mul_f32 v[64:65], v[62:63], s[14:15] op_sel_hi:[1,0]
	v_exp_f32_e32 v66, v66
	v_exp_f32_e32 v67, v67
	v_exp_f32_e32 v70, v70
	v_exp_f32_e32 v68, v68
	v_exp_f32_e32 v69, v69
	v_exp_f32_e32 v71, v71
	v_exp_f32_e32 v64, v64
	v_exp_f32_e32 v65, v65
	v_pk_add_f32 v[66:67], v[66:67], 1.0 op_sel_hi:[1,0]
	v_pk_add_f32 v[68:69], v[68:69], 1.0 op_sel_hi:[1,0]
	v_pk_add_f32 v[70:71], v[70:71], 1.0 op_sel_hi:[1,0]
	v_rcp_f32_e32 v66, v66
	v_rcp_f32_e32 v67, v67
	v_pk_add_f32 v[64:65], v[64:65], 1.0 op_sel_hi:[1,0]
	v_rcp_f32_e32 v70, v70
	v_rcp_f32_e32 v71, v71
	v_rcp_f32_e32 v68, v68
	v_rcp_f32_e32 v69, v69
	v_rcp_f32_e32 v64, v64
	v_rcp_f32_e32 v65, v65
	v_pk_mul_f32 v[52:53], v[66:67], v[52:53]
	v_pk_mul_f32 v[50:51], v[58:59], v[50:51]
	v_pk_mul_f32 v[48:49], v[56:57], v[48:49]
	s_movk_i32 s8, 0x4000
	v_pk_mul_f32 v[54:55], v[62:63], v[54:55]
	v_pk_mul_f32 v[56:57], v[68:69], v[50:51]
	v_pk_mul_f32 v[50:51], v[70:71], v[48:49]
	v_cvt_pk_bf16_f32 v48, v52, v53
	v_add_co_u32_e32 v52, vcc, s8, v144
	v_pk_mul_f32 v[54:55], v[64:65], v[54:55]
	s_nop 0
	v_addc_co_u32_e32 v53, vcc, 0, v145, vcc
	s_movk_i32 s8, 0x5000
	v_cvt_pk_bf16_f32 v49, v54, v55
	v_add_co_u32_e32 v54, vcc, s8, v144
	v_cvt_pk_bf16_f32 v50, v50, v51
	v_cvt_pk_bf16_f32 v51, v56, v57
	v_pk_mul_f32 v[56:57], v[42:43], s[14:15] op_sel_hi:[1,0]
	s_nop 0
	v_addc_co_u32_e32 v55, vcc, 0, v145, vcc
	v_pk_mul_f32 v[58:59], v[40:41], s[14:15] op_sel_hi:[1,0]
	global_store_dwordx4 v[54:55], v[48:51], off offset:-4096 nt
	v_exp_f32_e32 v58, v58
	v_exp_f32_e32 v56, v56
	v_pk_mul_f32 v[48:49], v[46:47], s[14:15] op_sel_hi:[1,0]
	v_pk_mul_f32 v[50:51], v[44:45], s[14:15] op_sel_hi:[1,0]
	v_exp_f32_e32 v57, v57
	v_exp_f32_e32 v59, v59
	v_exp_f32_e32 v50, v50
	v_exp_f32_e32 v51, v51
	v_exp_f32_e32 v48, v48
	v_exp_f32_e32 v49, v49
	v_pk_add_f32 v[56:57], v[56:57], 1.0 op_sel_hi:[1,0]
	v_pk_add_f32 v[58:59], v[58:59], 1.0 op_sel_hi:[1,0]
	v_pk_add_f32 v[50:51], v[50:51], 1.0 op_sel_hi:[1,0]
	v_pk_add_f32 v[48:49], v[48:49], 1.0 op_sel_hi:[1,0]
	v_rcp_f32_e32 v58, v58
	v_rcp_f32_e32 v59, v59
	v_rcp_f32_e32 v56, v56
	v_rcp_f32_e32 v57, v57
	v_rcp_f32_e32 v50, v50
	v_rcp_f32_e32 v51, v51
	v_rcp_f32_e32 v48, v48
	v_rcp_f32_e32 v49, v49
	v_pk_mul_f32 v[34:35], v[42:43], v[34:35]
	v_pk_mul_f32 v[32:33], v[40:41], v[32:33]
	v_pk_mul_f32 v[38:39], v[46:47], v[38:39]
	v_pk_mul_f32 v[36:37], v[44:45], v[36:37]
	v_pk_mul_f32 v[40:41], v[56:57], v[34:35]
	v_pk_mul_f32 v[34:35], v[58:59], v[32:33]
	v_pk_mul_f32 v[38:39], v[48:49], v[38:39]
	v_pk_mul_f32 v[36:37], v[50:51], v[36:37]
	v_pk_mul_f32 v[22:23], v[30:31], v[22:23]
	v_cvt_pk_bf16_f32 v32, v36, v37
	v_cvt_pk_bf16_f32 v33, v38, v39
	v_cvt_pk_bf16_f32 v34, v34, v35
	v_cvt_pk_bf16_f32 v35, v40, v41
	global_store_dwordx4 v[52:53], v[32:35], off offset:2048 nt
	v_pk_mul_f32 v[36:37], v[26:27], s[14:15] op_sel_hi:[1,0]
	v_pk_mul_f32 v[38:39], v[24:25], s[14:15] op_sel_hi:[1,0]
	v_pk_mul_f32 v[32:33], v[30:31], s[14:15] op_sel_hi:[1,0]
	v_pk_mul_f32 v[34:35], v[28:29], s[14:15] op_sel_hi:[1,0]
	v_exp_f32_e32 v38, v38
	v_exp_f32_e32 v34, v34
	v_exp_f32_e32 v35, v35
	v_exp_f32_e32 v32, v32
	v_exp_f32_e32 v33, v33
	v_exp_f32_e32 v36, v36
	v_exp_f32_e32 v37, v37
	v_exp_f32_e32 v39, v39
	v_pk_add_f32 v[32:33], v[32:33], 1.0 op_sel_hi:[1,0]
	v_pk_add_f32 v[34:35], v[34:35], 1.0 op_sel_hi:[1,0]
	v_pk_add_f32 v[36:37], v[36:37], 1.0 op_sel_hi:[1,0]
	v_pk_add_f32 v[38:39], v[38:39], 1.0 op_sel_hi:[1,0]
	v_rcp_f32_e32 v34, v34
	v_rcp_f32_e32 v38, v38
	v_rcp_f32_e32 v35, v35
	v_rcp_f32_e32 v39, v39
	v_rcp_f32_e32 v32, v32
	v_rcp_f32_e32 v36, v36
	v_rcp_f32_e32 v33, v33
	v_rcp_f32_e32 v37, v37
	v_pk_mul_f32 v[20:21], v[28:29], v[20:21]
	v_pk_mul_f32 v[18:19], v[26:27], v[18:19]
	v_pk_mul_f32 v[16:17], v[24:25], v[16:17]
	v_pk_mul_f32 v[22:23], v[32:33], v[22:23]
	v_pk_mul_f32 v[20:21], v[34:35], v[20:21]
	v_pk_mul_f32 v[24:25], v[36:37], v[18:19]
	v_pk_mul_f32 v[18:19], v[38:39], v[16:17]
	v_cvt_pk_bf16_f32 v16, v20, v21
	v_cvt_pk_bf16_f32 v17, v22, v23
	v_pk_mul_f32 v[20:21], v[10:11], s[14:15] op_sel_hi:[1,0]
	v_cvt_pk_bf16_f32 v18, v18, v19
	v_cvt_pk_bf16_f32 v19, v24, v25
	v_pk_mul_f32 v[22:23], v[8:9], s[14:15] op_sel_hi:[1,0]
	global_store_dwordx4 v[54:55], v[16:19], off nt
	v_exp_f32_e32 v22, v22
	v_exp_f32_e32 v20, v20
	v_pk_mul_f32 v[16:17], v[14:15], s[14:15] op_sel_hi:[1,0]
	v_pk_mul_f32 v[18:19], v[12:13], s[14:15] op_sel_hi:[1,0]
	v_exp_f32_e32 v21, v21
	v_exp_f32_e32 v23, v23
	v_exp_f32_e32 v18, v18
	v_exp_f32_e32 v19, v19
	v_exp_f32_e32 v16, v16
	v_exp_f32_e32 v17, v17
	v_pk_add_f32 v[20:21], v[20:21], 1.0 op_sel_hi:[1,0]
	v_pk_add_f32 v[22:23], v[22:23], 1.0 op_sel_hi:[1,0]
	v_pk_add_f32 v[18:19], v[18:19], 1.0 op_sel_hi:[1,0]
	v_pk_add_f32 v[16:17], v[16:17], 1.0 op_sel_hi:[1,0]
	v_rcp_f32_e32 v22, v22
	v_rcp_f32_e32 v23, v23
	v_rcp_f32_e32 v20, v20
	v_rcp_f32_e32 v21, v21
	v_rcp_f32_e32 v18, v18
	v_rcp_f32_e32 v19, v19
	v_rcp_f32_e32 v16, v16
	v_rcp_f32_e32 v17, v17
	v_pk_mul_f32 v[2:3], v[10:11], v[2:3]
	v_pk_mul_f32 v[0:1], v[8:9], v[0:1]
	v_pk_mul_f32 v[6:7], v[14:15], v[6:7]
	v_pk_mul_f32 v[4:5], v[12:13], v[4:5]
	v_pk_mul_f32 v[8:9], v[20:21], v[2:3]
	v_pk_mul_f32 v[2:3], v[22:23], v[0:1]
	s_andn2_b64 vcc, exec, s[6:7]
	s_mov_b64 s[6:7], -1
	v_pk_mul_f32 v[6:7], v[16:17], v[6:7]
	v_pk_mul_f32 v[4:5], v[18:19], v[4:5]
	s_nop 0
	v_cvt_pk_bf16_f32 v0, v4, v5
	v_cvt_pk_bf16_f32 v1, v6, v7
	v_cvt_pk_bf16_f32 v2, v2, v3
	v_cvt_pk_bf16_f32 v3, v8, v9
	global_store_dwordx4 v[54:55], v[0:3], off offset:2048 nt
	s_cbranch_vccnz .LBB0_1624
	s_andn2_b64 vcc, exec, s[10:11]
	s_cbranch_vccnz .LBB0_1623
	s_barrier
	s_branch .LBB0_1623

.LBB0_1825:
	v_mov_b32_e32 v144, v146
	s_mov_b32 s17, s15
	v_mov_b32_e32 v152, v147
	s_mov_b32 s19, s38
	s_lshl_b32 s24, s45, 1
	s_ashr_i32 s25, s19, 1
	s_add_i32 s24, s25, s24
	s_ashr_i32 s25, s24, 31
	s_lshl_b64 s[24:25], s[24:25], 22
	s_add_u32 s24, s60, s24
	s_addc_u32 s25, s61, s25
	s_lshl_b32 s8, s8, 8
	s_lshl_b32 s17, s17, 6
	s_add_i32 s17, s17, s8
	v_add_u32_e32 v144, s17, v144
	v_ashrrev_i32_e32 v145, 31, v144
	v_lshlrev_b64 v[144:145], 7, v[144:145]
	s_lshl_b32 s8, s19, 6
	v_lshl_add_u64 v[144:145], s[24:25], 0, v[144:145]
	s_and_b32 s8, s8, 64
	v_lshlrev_b32_e32 v152, 3, v152
	v_lshl_add_u64 v[144:145], v[144:145], 0, s[8:9]
	v_ashrrev_i32_e32 v153, 31, v152
	v_lshl_add_u64 v[144:145], v[152:153], 1, v[144:145]
	v_pk_mul_f32 v[152:153], v[126:127], s[14:15] op_sel_hi:[1,0]
	v_pk_mul_f32 v[154:155], v[124:125], s[14:15] op_sel_hi:[1,0]
	v_pk_mul_f32 v[156:157], v[122:123], s[14:15] op_sel_hi:[1,0]
	v_pk_mul_f32 v[158:159], v[120:121], s[14:15] op_sel_hi:[1,0]
	v_exp_f32_e32 v154, v154
	v_exp_f32_e32 v158, v158
	v_exp_f32_e32 v155, v155
	v_exp_f32_e32 v152, v152
	v_exp_f32_e32 v153, v153
	v_exp_f32_e32 v156, v156
	v_exp_f32_e32 v157, v157
	v_exp_f32_e32 v159, v159
	v_pk_add_f32 v[152:153], v[152:153], 1.0 op_sel_hi:[1,0]
	v_pk_add_f32 v[154:155], v[154:155], 1.0 op_sel_hi:[1,0]
	v_pk_add_f32 v[156:157], v[156:157], 1.0 op_sel_hi:[1,0]
	v_pk_add_f32 v[158:159], v[158:159], 1.0 op_sel_hi:[1,0]
	v_rcp_f32_e32 v154, v154
	v_rcp_f32_e32 v158, v158
	v_rcp_f32_e32 v155, v155
	v_rcp_f32_e32 v159, v159
	v_rcp_f32_e32 v152, v152
	v_rcp_f32_e32 v156, v156
	v_rcp_f32_e32 v153, v153
	v_rcp_f32_e32 v157, v157
	v_pk_mul_f32 v[118:119], v[126:127], v[118:119]
	v_pk_mul_f32 v[116:117], v[124:125], v[116:117]
	v_pk_mul_f32 v[114:115], v[122:123], v[114:115]
	v_pk_mul_f32 v[112:113], v[120:121], v[112:113]
	v_pk_mul_f32 v[118:119], v[152:153], v[118:119]
	v_pk_mul_f32 v[116:117], v[154:155], v[116:117]
	v_pk_mul_f32 v[120:121], v[156:157], v[114:115]
	v_pk_mul_f32 v[114:115], v[158:159], v[112:113]
	v_cvt_pk_bf16_f32 v112, v116, v117
	v_cvt_pk_bf16_f32 v113, v118, v119
	v_pk_mul_f32 v[116:117], v[106:107], s[14:15] op_sel_hi:[1,0]
	v_cvt_pk_bf16_f32 v114, v114, v115
	v_cvt_pk_bf16_f32 v115, v120, v121
	v_pk_mul_f32 v[118:119], v[104:105], s[14:15] op_sel_hi:[1,0]
	global_store_dwordx4 v[144:145], v[112:115], off nt
	v_exp_f32_e32 v118, v118
	v_exp_f32_e32 v116, v116
	v_pk_mul_f32 v[112:113], v[110:111], s[14:15] op_sel_hi:[1,0]
	v_pk_mul_f32 v[114:115], v[108:109], s[14:15] op_sel_hi:[1,0]
	v_exp_f32_e32 v117, v117
	v_exp_f32_e32 v119, v119
	v_exp_f32_e32 v114, v114
	v_exp_f32_e32 v115, v115
	v_exp_f32_e32 v112, v112
	v_exp_f32_e32 v113, v113
	v_pk_add_f32 v[116:117], v[116:117], 1.0 op_sel_hi:[1,0]
	v_pk_add_f32 v[118:119], v[118:119], 1.0 op_sel_hi:[1,0]
	v_pk_add_f32 v[114:115], v[114:115], 1.0 op_sel_hi:[1,0]
	v_pk_add_f32 v[112:113], v[112:113], 1.0 op_sel_hi:[1,0]
	v_rcp_f32_e32 v118, v118
	v_rcp_f32_e32 v119, v119
	v_rcp_f32_e32 v116, v116
	v_rcp_f32_e32 v117, v117
	v_rcp_f32_e32 v114, v114
	v_rcp_f32_e32 v115, v115
	v_rcp_f32_e32 v112, v112
	v_rcp_f32_e32 v113, v113
	v_pk_mul_f32 v[98:99], v[106:107], v[98:99]
	v_pk_mul_f32 v[96:97], v[104:105], v[96:97]
	v_pk_mul_f32 v[102:103], v[110:111], v[102:103]
	v_pk_mul_f32 v[100:101], v[108:109], v[100:101]
	v_pk_mul_f32 v[104:105], v[116:117], v[98:99]
	v_pk_mul_f32 v[98:99], v[118:119], v[96:97]
	v_pk_mul_f32 v[102:103], v[112:113], v[102:103]
	v_pk_mul_f32 v[100:101], v[114:115], v[100:101]
	v_pk_mul_f32 v[84:85], v[92:93], v[84:85]
	v_cvt_pk_bf16_f32 v96, v100, v101
	v_cvt_pk_bf16_f32 v97, v102, v103
	v_cvt_pk_bf16_f32 v98, v98, v99
	v_cvt_pk_bf16_f32 v99, v104, v105
	global_store_dwordx4 v[144:145], v[96:99], off offset:2048 nt
	v_pk_mul_f32 v[100:101], v[90:91], s[14:15] op_sel_hi:[1,0]
	v_pk_mul_f32 v[102:103], v[88:89], s[14:15] op_sel_hi:[1,0]
	v_pk_mul_f32 v[98:99], v[92:93], s[14:15] op_sel_hi:[1,0]
	v_pk_mul_f32 v[96:97], v[94:95], s[14:15] op_sel_hi:[1,0]
	v_exp_f32_e32 v98, v98
	v_exp_f32_e32 v99, v99
	v_exp_f32_e32 v102, v102
	v_exp_f32_e32 v96, v96
	v_exp_f32_e32 v97, v97
	v_exp_f32_e32 v100, v100
	v_exp_f32_e32 v101, v101
	v_exp_f32_e32 v103, v103
	v_pk_add_f32 v[98:99], v[98:99], 1.0 op_sel_hi:[1,0]
	v_pk_add_f32 v[96:97], v[96:97], 1.0 op_sel_hi:[1,0]
	v_pk_add_f32 v[100:101], v[100:101], 1.0 op_sel_hi:[1,0]
	v_pk_add_f32 v[102:103], v[102:103], 1.0 op_sel_hi:[1,0]
	v_rcp_f32_e32 v98, v98
	v_rcp_f32_e32 v99, v99
	v_rcp_f32_e32 v102, v102
	v_rcp_f32_e32 v103, v103
	v_rcp_f32_e32 v96, v96
	v_rcp_f32_e32 v100, v100
	v_rcp_f32_e32 v97, v97
	v_rcp_f32_e32 v101, v101
	v_pk_mul_f32 v[86:87], v[94:95], v[86:87]
	v_pk_mul_f32 v[84:85], v[98:99], v[84:85]
	v_pk_mul_f32 v[82:83], v[90:91], v[82:83]
	v_pk_mul_f32 v[80:81], v[88:89], v[80:81]
	s_movk_i32 s8, 0x1000
	v_pk_mul_f32 v[86:87], v[96:97], v[86:87]
	v_pk_mul_f32 v[88:89], v[100:101], v[82:83]
	v_pk_mul_f32 v[82:83], v[102:103], v[80:81]
	v_cvt_pk_bf16_f32 v80, v84, v85
	v_add_co_u32_e32 v84, vcc, s8, v144
	v_cvt_pk_bf16_f32 v81, v86, v87
	v_cvt_pk_bf16_f32 v82, v82, v83
	v_cvt_pk_bf16_f32 v83, v88, v89
	v_pk_mul_f32 v[86:87], v[74:75], s[14:15] op_sel_hi:[1,0]
	s_nop 0
	v_addc_co_u32_e32 v85, vcc, 0, v145, vcc
	v_pk_mul_f32 v[88:89], v[72:73], s[14:15] op_sel_hi:[1,0]
	global_store_dwordx4 v[84:85], v[80:83], off nt
	v_exp_f32_e32 v88, v88
	v_exp_f32_e32 v86, v86
	v_pk_mul_f32 v[80:81], v[78:79], s[14:15] op_sel_hi:[1,0]
	v_pk_mul_f32 v[82:83], v[76:77], s[14:15] op_sel_hi:[1,0]
	v_exp_f32_e32 v87, v87
	v_exp_f32_e32 v89, v89
	v_exp_f32_e32 v82, v82
	v_exp_f32_e32 v83, v83
	v_exp_f32_e32 v80, v80
	v_exp_f32_e32 v81, v81
	v_pk_add_f32 v[86:87], v[86:87], 1.0 op_sel_hi:[1,0]
	v_pk_add_f32 v[88:89], v[88:89], 1.0 op_sel_hi:[1,0]
	v_pk_add_f32 v[82:83], v[82:83], 1.0 op_sel_hi:[1,0]
	v_pk_add_f32 v[80:81], v[80:81], 1.0 op_sel_hi:[1,0]
	v_rcp_f32_e32 v88, v88
	v_rcp_f32_e32 v89, v89
	v_rcp_f32_e32 v86, v86
	v_rcp_f32_e32 v87, v87
	v_rcp_f32_e32 v82, v82
	v_rcp_f32_e32 v83, v83
	v_rcp_f32_e32 v80, v80
	v_rcp_f32_e32 v81, v81
	v_pk_mul_f32 v[66:67], v[74:75], v[66:67]
	v_pk_mul_f32 v[64:65], v[72:73], v[64:65]
	v_pk_mul_f32 v[70:71], v[78:79], v[70:71]
	v_pk_mul_f32 v[68:69], v[76:77], v[68:69]
	v_pk_mul_f32 v[72:73], v[86:87], v[66:67]
	v_pk_mul_f32 v[66:67], v[88:89], v[64:65]
	v_pk_mul_f32 v[70:71], v[80:81], v[70:71]
	v_pk_mul_f32 v[68:69], v[82:83], v[68:69]
	v_pk_mul_f32 v[52:53], v[60:61], v[52:53]
	v_cvt_pk_bf16_f32 v64, v68, v69
	v_cvt_pk_bf16_f32 v65, v70, v71
	v_cvt_pk_bf16_f32 v66, v66, v67
	v_cvt_pk_bf16_f32 v67, v72, v73
	global_store_dwordx4 v[84:85], v[64:67], off offset:2048 nt
	v_pk_mul_f32 v[68:69], v[58:59], s[14:15] op_sel_hi:[1,0]
	v_pk_mul_f32 v[70:71], v[56:57], s[14:15] op_sel_hi:[1,0]
	v_pk_mul_f32 v[66:67], v[60:61], s[14:15] op_sel_hi:[1,0]
	v_pk_mul_f32 v[64:65], v[62:63], s[14:15] op_sel_hi:[1,0]
	v_exp_f32_e32 v66, v66
	v_exp_f32_e32 v67, v67
	v_exp_f32_e32 v70, v70
	v_exp_f32_e32 v68, v68
	v_exp_f32_e32 v69, v69
	v_exp_f32_e32 v71, v71
	v_exp_f32_e32 v64, v64
	v_exp_f32_e32 v65, v65
	v_pk_add_f32 v[66:67], v[66:67], 1.0 op_sel_hi:[1,0]
	v_pk_add_f32 v[68:69], v[68:69], 1.0 op_sel_hi:[1,0]
	v_pk_add_f32 v[70:71], v[70:71], 1.0 op_sel_hi:[1,0]
	v_rcp_f32_e32 v66, v66
	v_rcp_f32_e32 v67, v67
	v_pk_add_f32 v[64:65], v[64:65], 1.0 op_sel_hi:[1,0]
	v_rcp_f32_e32 v70, v70
	v_rcp_f32_e32 v71, v71
	v_rcp_f32_e32 v68, v68
	v_rcp_f32_e32 v69, v69
	v_rcp_f32_e32 v64, v64
	v_rcp_f32_e32 v65, v65
	v_pk_mul_f32 v[52:53], v[66:67], v[52:53]
	v_pk_mul_f32 v[50:51], v[58:59], v[50:51]
	v_pk_mul_f32 v[48:49], v[56:57], v[48:49]
	s_movk_i32 s8, 0x4000
	v_pk_mul_f32 v[54:55], v[62:63], v[54:55]
	v_pk_mul_f32 v[56:57], v[68:69], v[50:51]
	v_pk_mul_f32 v[50:51], v[70:71], v[48:49]
	v_cvt_pk_bf16_f32 v48, v52, v53
	v_add_co_u32_e32 v52, vcc, s8, v144
	v_pk_mul_f32 v[54:55], v[64:65], v[54:55]
	s_nop 0
	v_addc_co_u32_e32 v53, vcc, 0, v145, vcc
	s_movk_i32 s8, 0x5000
	v_cvt_pk_bf16_f32 v49, v54, v55
	v_add_co_u32_e32 v54, vcc, s8, v144
	v_cvt_pk_bf16_f32 v50, v50, v51
	v_cvt_pk_bf16_f32 v51, v56, v57
	v_pk_mul_f32 v[56:57], v[42:43], s[14:15] op_sel_hi:[1,0]
	s_nop 0
	v_addc_co_u32_e32 v55, vcc, 0, v145, vcc
	v_pk_mul_f32 v[58:59], v[40:41], s[14:15] op_sel_hi:[1,0]
	global_store_dwordx4 v[54:55], v[48:51], off offset:-4096 nt
	v_exp_f32_e32 v58, v58
	v_exp_f32_e32 v56, v56
	v_pk_mul_f32 v[48:49], v[46:47], s[14:15] op_sel_hi:[1,0]
	v_pk_mul_f32 v[50:51], v[44:45], s[14:15] op_sel_hi:[1,0]
	v_exp_f32_e32 v57, v57
	v_exp_f32_e32 v59, v59
	v_exp_f32_e32 v50, v50
	v_exp_f32_e32 v51, v51
	v_exp_f32_e32 v48, v48
	v_exp_f32_e32 v49, v49
	v_pk_add_f32 v[56:57], v[56:57], 1.0 op_sel_hi:[1,0]
	v_pk_add_f32 v[58:59], v[58:59], 1.0 op_sel_hi:[1,0]
	v_pk_add_f32 v[50:51], v[50:51], 1.0 op_sel_hi:[1,0]
	v_pk_add_f32 v[48:49], v[48:49], 1.0 op_sel_hi:[1,0]
	v_rcp_f32_e32 v58, v58
	v_rcp_f32_e32 v59, v59
	v_rcp_f32_e32 v56, v56
	v_rcp_f32_e32 v57, v57
	v_rcp_f32_e32 v50, v50
	v_rcp_f32_e32 v51, v51
	v_rcp_f32_e32 v48, v48
	v_rcp_f32_e32 v49, v49
	v_pk_mul_f32 v[34:35], v[42:43], v[34:35]
	v_pk_mul_f32 v[32:33], v[40:41], v[32:33]
	v_pk_mul_f32 v[38:39], v[46:47], v[38:39]
	v_pk_mul_f32 v[36:37], v[44:45], v[36:37]
	v_pk_mul_f32 v[40:41], v[56:57], v[34:35]
	v_pk_mul_f32 v[34:35], v[58:59], v[32:33]
	v_pk_mul_f32 v[38:39], v[48:49], v[38:39]
	v_pk_mul_f32 v[36:37], v[50:51], v[36:37]
	v_pk_mul_f32 v[22:23], v[30:31], v[22:23]
	v_cvt_pk_bf16_f32 v32, v36, v37
	v_cvt_pk_bf16_f32 v33, v38, v39
	v_cvt_pk_bf16_f32 v34, v34, v35
	v_cvt_pk_bf16_f32 v35, v40, v41
	global_store_dwordx4 v[52:53], v[32:35], off offset:2048 nt
	v_pk_mul_f32 v[36:37], v[26:27], s[14:15] op_sel_hi:[1,0]
	v_pk_mul_f32 v[38:39], v[24:25], s[14:15] op_sel_hi:[1,0]
	v_pk_mul_f32 v[32:33], v[30:31], s[14:15] op_sel_hi:[1,0]
	v_pk_mul_f32 v[34:35], v[28:29], s[14:15] op_sel_hi:[1,0]
	v_exp_f32_e32 v38, v38
	v_exp_f32_e32 v34, v34
	v_exp_f32_e32 v35, v35
	v_exp_f32_e32 v32, v32
	v_exp_f32_e32 v33, v33
	v_exp_f32_e32 v36, v36
	v_exp_f32_e32 v37, v37
	v_exp_f32_e32 v39, v39
	v_pk_add_f32 v[32:33], v[32:33], 1.0 op_sel_hi:[1,0]
	v_pk_add_f32 v[34:35], v[34:35], 1.0 op_sel_hi:[1,0]
	v_pk_add_f32 v[36:37], v[36:37], 1.0 op_sel_hi:[1,0]
	v_pk_add_f32 v[38:39], v[38:39], 1.0 op_sel_hi:[1,0]
	v_rcp_f32_e32 v34, v34
	v_rcp_f32_e32 v38, v38
	v_rcp_f32_e32 v35, v35
	v_rcp_f32_e32 v39, v39
	v_rcp_f32_e32 v32, v32
	v_rcp_f32_e32 v36, v36
	v_rcp_f32_e32 v33, v33
	v_rcp_f32_e32 v37, v37
	v_pk_mul_f32 v[20:21], v[28:29], v[20:21]
	v_pk_mul_f32 v[18:19], v[26:27], v[18:19]
	v_pk_mul_f32 v[16:17], v[24:25], v[16:17]
	v_pk_mul_f32 v[22:23], v[32:33], v[22:23]
	v_pk_mul_f32 v[20:21], v[34:35], v[20:21]
	v_pk_mul_f32 v[24:25], v[36:37], v[18:19]
	v_pk_mul_f32 v[18:19], v[38:39], v[16:17]
	v_cvt_pk_bf16_f32 v16, v20, v21
	v_cvt_pk_bf16_f32 v17, v22, v23
	v_pk_mul_f32 v[20:21], v[10:11], s[14:15] op_sel_hi:[1,0]
	v_cvt_pk_bf16_f32 v18, v18, v19
	v_cvt_pk_bf16_f32 v19, v24, v25
	v_pk_mul_f32 v[22:23], v[8:9], s[14:15] op_sel_hi:[1,0]
	global_store_dwordx4 v[54:55], v[16:19], off nt
	v_exp_f32_e32 v22, v22
	v_exp_f32_e32 v20, v20
	v_pk_mul_f32 v[16:17], v[14:15], s[14:15] op_sel_hi:[1,0]
	v_pk_mul_f32 v[18:19], v[12:13], s[14:15] op_sel_hi:[1,0]
	v_exp_f32_e32 v21, v21
	v_exp_f32_e32 v23, v23
	v_exp_f32_e32 v18, v18
	v_exp_f32_e32 v19, v19
	v_exp_f32_e32 v16, v16
	v_exp_f32_e32 v17, v17
	v_pk_add_f32 v[20:21], v[20:21], 1.0 op_sel_hi:[1,0]
	v_pk_add_f32 v[22:23], v[22:23], 1.0 op_sel_hi:[1,0]
	v_pk_add_f32 v[18:19], v[18:19], 1.0 op_sel_hi:[1,0]
	v_pk_add_f32 v[16:17], v[16:17], 1.0 op_sel_hi:[1,0]
	v_rcp_f32_e32 v22, v22
	v_rcp_f32_e32 v23, v23
	v_rcp_f32_e32 v20, v20
	v_rcp_f32_e32 v21, v21
	v_rcp_f32_e32 v18, v18
	v_rcp_f32_e32 v19, v19
	v_rcp_f32_e32 v16, v16
	v_rcp_f32_e32 v17, v17
	v_pk_mul_f32 v[2:3], v[10:11], v[2:3]
	v_pk_mul_f32 v[0:1], v[8:9], v[0:1]
	v_pk_mul_f32 v[6:7], v[14:15], v[6:7]
	v_pk_mul_f32 v[4:5], v[12:13], v[4:5]
	v_pk_mul_f32 v[8:9], v[20:21], v[2:3]
	v_pk_mul_f32 v[2:3], v[22:23], v[0:1]
	s_andn2_b64 vcc, exec, s[6:7]
	s_mov_b64 s[6:7], -1
	v_pk_mul_f32 v[6:7], v[16:17], v[6:7]
	v_pk_mul_f32 v[4:5], v[18:19], v[4:5]
	s_nop 0
	v_cvt_pk_bf16_f32 v0, v4, v5
	v_cvt_pk_bf16_f32 v1, v6, v7
	v_cvt_pk_bf16_f32 v2, v2, v3
	v_cvt_pk_bf16_f32 v3, v8, v9
	global_store_dwordx4 v[54:55], v[0:3], off offset:2048 nt
	s_cbranch_vccnz .LBB0_1818
	s_andn2_b64 vcc, exec, s[10:11]
	s_cbranch_vccnz .LBB0_1817
	s_barrier
	s_branch .LBB0_1817

.LBB0_2891:
	v_mov_b32_e32 v144, v146
	s_mov_b32 s15, s13
	v_mov_b32_e32 v152, v147
	s_mov_b32 s17, s37
	s_lshl_b32 s22, s47, 1
	s_ashr_i32 s23, s17, 1
	s_add_i32 s22, s23, s22
	s_ashr_i32 s23, s22, 31
	s_lshl_b64 s[22:23], s[22:23], 22
	s_add_u32 s22, s60, s22
	s_addc_u32 s23, s61, s23
	s_lshl_b32 s6, s6, 8
	s_lshl_b32 s15, s15, 6
	s_add_i32 s15, s15, s6
	v_add_u32_e32 v144, s15, v144
	v_ashrrev_i32_e32 v145, 31, v144
	v_lshlrev_b64 v[144:145], 7, v[144:145]
	s_lshl_b32 s6, s17, 6
	v_lshl_add_u64 v[144:145], s[22:23], 0, v[144:145]
	s_and_b32 s6, s6, 64
	v_lshlrev_b32_e32 v152, 3, v152
	v_lshl_add_u64 v[144:145], v[144:145], 0, s[6:7]
	v_ashrrev_i32_e32 v153, 31, v152
	v_lshl_add_u64 v[144:145], v[152:153], 1, v[144:145]
	v_pk_mul_f32 v[152:153], v[126:127], s[12:13] op_sel_hi:[1,0]
	v_pk_mul_f32 v[154:155], v[124:125], s[12:13] op_sel_hi:[1,0]
	v_pk_mul_f32 v[156:157], v[122:123], s[12:13] op_sel_hi:[1,0]
	v_pk_mul_f32 v[158:159], v[120:121], s[12:13] op_sel_hi:[1,0]
	v_exp_f32_e32 v154, v154
	v_exp_f32_e32 v158, v158
	v_exp_f32_e32 v155, v155
	v_exp_f32_e32 v152, v152
	v_exp_f32_e32 v153, v153
	v_exp_f32_e32 v156, v156
	v_exp_f32_e32 v157, v157
	v_exp_f32_e32 v159, v159
	v_pk_add_f32 v[152:153], v[152:153], 1.0 op_sel_hi:[1,0]
	v_pk_add_f32 v[154:155], v[154:155], 1.0 op_sel_hi:[1,0]
	v_pk_add_f32 v[156:157], v[156:157], 1.0 op_sel_hi:[1,0]
	v_pk_add_f32 v[158:159], v[158:159], 1.0 op_sel_hi:[1,0]
	v_rcp_f32_e32 v154, v154
	v_rcp_f32_e32 v158, v158
	v_rcp_f32_e32 v155, v155
	v_rcp_f32_e32 v159, v159
	v_rcp_f32_e32 v152, v152
	v_rcp_f32_e32 v156, v156
	v_rcp_f32_e32 v153, v153
	v_rcp_f32_e32 v157, v157
	v_pk_mul_f32 v[118:119], v[126:127], v[118:119]
	v_pk_mul_f32 v[116:117], v[124:125], v[116:117]
	v_pk_mul_f32 v[114:115], v[122:123], v[114:115]
	v_pk_mul_f32 v[112:113], v[120:121], v[112:113]
	v_pk_mul_f32 v[118:119], v[152:153], v[118:119]
	v_pk_mul_f32 v[116:117], v[154:155], v[116:117]
	v_pk_mul_f32 v[120:121], v[156:157], v[114:115]
	v_pk_mul_f32 v[114:115], v[158:159], v[112:113]
	v_cvt_pk_bf16_f32 v112, v116, v117
	v_cvt_pk_bf16_f32 v113, v118, v119
	v_pk_mul_f32 v[116:117], v[106:107], s[12:13] op_sel_hi:[1,0]
	v_cvt_pk_bf16_f32 v114, v114, v115
	v_cvt_pk_bf16_f32 v115, v120, v121
	v_pk_mul_f32 v[118:119], v[104:105], s[12:13] op_sel_hi:[1,0]
	global_store_dwordx4 v[144:145], v[112:115], off nt
	v_exp_f32_e32 v118, v118
	v_exp_f32_e32 v116, v116
	v_pk_mul_f32 v[112:113], v[110:111], s[12:13] op_sel_hi:[1,0]
	v_pk_mul_f32 v[114:115], v[108:109], s[12:13] op_sel_hi:[1,0]
	v_exp_f32_e32 v117, v117
	v_exp_f32_e32 v119, v119
	v_exp_f32_e32 v114, v114
	v_exp_f32_e32 v115, v115
	v_exp_f32_e32 v112, v112
	v_exp_f32_e32 v113, v113
	v_pk_add_f32 v[116:117], v[116:117], 1.0 op_sel_hi:[1,0]
	v_pk_add_f32 v[118:119], v[118:119], 1.0 op_sel_hi:[1,0]
	v_pk_add_f32 v[114:115], v[114:115], 1.0 op_sel_hi:[1,0]
	v_pk_add_f32 v[112:113], v[112:113], 1.0 op_sel_hi:[1,0]
	v_rcp_f32_e32 v118, v118
	v_rcp_f32_e32 v119, v119
	v_rcp_f32_e32 v116, v116
	v_rcp_f32_e32 v117, v117
	v_rcp_f32_e32 v114, v114
	v_rcp_f32_e32 v115, v115
	v_rcp_f32_e32 v112, v112
	v_rcp_f32_e32 v113, v113
	v_pk_mul_f32 v[98:99], v[106:107], v[98:99]
	v_pk_mul_f32 v[96:97], v[104:105], v[96:97]
	v_pk_mul_f32 v[102:103], v[110:111], v[102:103]
	v_pk_mul_f32 v[100:101], v[108:109], v[100:101]
	v_pk_mul_f32 v[104:105], v[116:117], v[98:99]
	v_pk_mul_f32 v[98:99], v[118:119], v[96:97]
	v_pk_mul_f32 v[102:103], v[112:113], v[102:103]
	v_pk_mul_f32 v[100:101], v[114:115], v[100:101]
	v_pk_mul_f32 v[84:85], v[92:93], v[84:85]
	v_cvt_pk_bf16_f32 v96, v100, v101
	v_cvt_pk_bf16_f32 v97, v102, v103
	v_cvt_pk_bf16_f32 v98, v98, v99
	v_cvt_pk_bf16_f32 v99, v104, v105
	global_store_dwordx4 v[144:145], v[96:99], off offset:2048 nt
	v_pk_mul_f32 v[100:101], v[90:91], s[12:13] op_sel_hi:[1,0]
	v_pk_mul_f32 v[102:103], v[88:89], s[12:13] op_sel_hi:[1,0]
	v_pk_mul_f32 v[98:99], v[92:93], s[12:13] op_sel_hi:[1,0]
	v_pk_mul_f32 v[96:97], v[94:95], s[12:13] op_sel_hi:[1,0]
	v_exp_f32_e32 v98, v98
	v_exp_f32_e32 v99, v99
	v_exp_f32_e32 v102, v102
	v_exp_f32_e32 v96, v96
	v_exp_f32_e32 v97, v97
	v_exp_f32_e32 v100, v100
	v_exp_f32_e32 v101, v101
	v_exp_f32_e32 v103, v103
	v_pk_add_f32 v[98:99], v[98:99], 1.0 op_sel_hi:[1,0]
	v_pk_add_f32 v[96:97], v[96:97], 1.0 op_sel_hi:[1,0]
	v_pk_add_f32 v[100:101], v[100:101], 1.0 op_sel_hi:[1,0]
	v_pk_add_f32 v[102:103], v[102:103], 1.0 op_sel_hi:[1,0]
	v_rcp_f32_e32 v98, v98
	v_rcp_f32_e32 v99, v99
	v_rcp_f32_e32 v102, v102
	v_rcp_f32_e32 v103, v103
	v_rcp_f32_e32 v96, v96
	v_rcp_f32_e32 v100, v100
	v_rcp_f32_e32 v97, v97
	v_rcp_f32_e32 v101, v101
	v_pk_mul_f32 v[86:87], v[94:95], v[86:87]
	v_pk_mul_f32 v[84:85], v[98:99], v[84:85]
	v_pk_mul_f32 v[82:83], v[90:91], v[82:83]
	v_pk_mul_f32 v[80:81], v[88:89], v[80:81]
	v_pk_mul_f32 v[86:87], v[96:97], v[86:87]
	v_pk_mul_f32 v[88:89], v[100:101], v[82:83]
	v_pk_mul_f32 v[82:83], v[102:103], v[80:81]
	v_cvt_pk_bf16_f32 v80, v84, v85
	v_add_co_u32_e32 v84, vcc, s42, v144
	v_cvt_pk_bf16_f32 v81, v86, v87
	v_cvt_pk_bf16_f32 v82, v82, v83
	v_cvt_pk_bf16_f32 v83, v88, v89
	v_pk_mul_f32 v[86:87], v[74:75], s[12:13] op_sel_hi:[1,0]
	s_nop 0
	v_addc_co_u32_e32 v85, vcc, 0, v145, vcc
	v_pk_mul_f32 v[88:89], v[72:73], s[12:13] op_sel_hi:[1,0]
	global_store_dwordx4 v[84:85], v[80:83], off nt
	v_exp_f32_e32 v88, v88
	v_exp_f32_e32 v86, v86
	v_pk_mul_f32 v[80:81], v[78:79], s[12:13] op_sel_hi:[1,0]
	v_pk_mul_f32 v[82:83], v[76:77], s[12:13] op_sel_hi:[1,0]
	v_exp_f32_e32 v87, v87
	v_exp_f32_e32 v89, v89
	v_exp_f32_e32 v82, v82
	v_exp_f32_e32 v83, v83
	v_exp_f32_e32 v80, v80
	v_exp_f32_e32 v81, v81
	v_pk_add_f32 v[86:87], v[86:87], 1.0 op_sel_hi:[1,0]
	v_pk_add_f32 v[88:89], v[88:89], 1.0 op_sel_hi:[1,0]
	v_pk_add_f32 v[82:83], v[82:83], 1.0 op_sel_hi:[1,0]
	v_pk_add_f32 v[80:81], v[80:81], 1.0 op_sel_hi:[1,0]
	v_rcp_f32_e32 v88, v88
	v_rcp_f32_e32 v89, v89
	v_rcp_f32_e32 v86, v86
	v_rcp_f32_e32 v87, v87
	v_rcp_f32_e32 v82, v82
	v_rcp_f32_e32 v83, v83
	v_rcp_f32_e32 v80, v80
	v_rcp_f32_e32 v81, v81
	v_pk_mul_f32 v[66:67], v[74:75], v[66:67]
	v_pk_mul_f32 v[64:65], v[72:73], v[64:65]
	v_pk_mul_f32 v[70:71], v[78:79], v[70:71]
	v_pk_mul_f32 v[68:69], v[76:77], v[68:69]
	v_pk_mul_f32 v[72:73], v[86:87], v[66:67]
	v_pk_mul_f32 v[66:67], v[88:89], v[64:65]
	v_pk_mul_f32 v[70:71], v[80:81], v[70:71]
	v_pk_mul_f32 v[68:69], v[82:83], v[68:69]
	v_pk_mul_f32 v[52:53], v[60:61], v[52:53]
	v_cvt_pk_bf16_f32 v64, v68, v69
	v_cvt_pk_bf16_f32 v65, v70, v71
	v_cvt_pk_bf16_f32 v66, v66, v67
	v_cvt_pk_bf16_f32 v67, v72, v73
	global_store_dwordx4 v[84:85], v[64:67], off offset:2048 nt
	v_pk_mul_f32 v[68:69], v[58:59], s[12:13] op_sel_hi:[1,0]
	v_pk_mul_f32 v[70:71], v[56:57], s[12:13] op_sel_hi:[1,0]
	v_pk_mul_f32 v[66:67], v[60:61], s[12:13] op_sel_hi:[1,0]
	v_pk_mul_f32 v[64:65], v[62:63], s[12:13] op_sel_hi:[1,0]
	v_exp_f32_e32 v66, v66
	v_exp_f32_e32 v67, v67
	v_exp_f32_e32 v70, v70
	v_exp_f32_e32 v68, v68
	v_exp_f32_e32 v69, v69
	v_exp_f32_e32 v71, v71
	v_exp_f32_e32 v64, v64
	v_exp_f32_e32 v65, v65
	v_pk_add_f32 v[66:67], v[66:67], 1.0 op_sel_hi:[1,0]
	v_pk_add_f32 v[68:69], v[68:69], 1.0 op_sel_hi:[1,0]
	v_pk_add_f32 v[70:71], v[70:71], 1.0 op_sel_hi:[1,0]
	v_rcp_f32_e32 v66, v66
	v_rcp_f32_e32 v67, v67
	v_pk_add_f32 v[64:65], v[64:65], 1.0 op_sel_hi:[1,0]
	v_rcp_f32_e32 v70, v70
	v_rcp_f32_e32 v71, v71
	v_rcp_f32_e32 v68, v68
	v_rcp_f32_e32 v69, v69
	v_rcp_f32_e32 v64, v64
	v_rcp_f32_e32 v65, v65
	v_pk_mul_f32 v[52:53], v[66:67], v[52:53]
	v_pk_mul_f32 v[50:51], v[58:59], v[50:51]
	v_pk_mul_f32 v[48:49], v[56:57], v[48:49]
	v_pk_mul_f32 v[54:55], v[62:63], v[54:55]
	v_pk_mul_f32 v[56:57], v[68:69], v[50:51]
	v_pk_mul_f32 v[50:51], v[70:71], v[48:49]
	v_cvt_pk_bf16_f32 v48, v52, v53
	v_add_co_u32_e32 v52, vcc, s36, v144
	v_pk_mul_f32 v[54:55], v[64:65], v[54:55]
	s_nop 0
	v_addc_co_u32_e32 v53, vcc, 0, v145, vcc
	v_cvt_pk_bf16_f32 v49, v54, v55
	v_add_co_u32_e32 v54, vcc, s43, v144
	v_cvt_pk_bf16_f32 v50, v50, v51
	v_cvt_pk_bf16_f32 v51, v56, v57
	v_pk_mul_f32 v[56:57], v[42:43], s[12:13] op_sel_hi:[1,0]
	s_nop 0
	v_addc_co_u32_e32 v55, vcc, 0, v145, vcc
	v_pk_mul_f32 v[58:59], v[40:41], s[12:13] op_sel_hi:[1,0]
	global_store_dwordx4 v[54:55], v[48:51], off offset:-4096 nt
	v_exp_f32_e32 v58, v58
	v_exp_f32_e32 v56, v56
	v_pk_mul_f32 v[48:49], v[46:47], s[12:13] op_sel_hi:[1,0]
	v_pk_mul_f32 v[50:51], v[44:45], s[12:13] op_sel_hi:[1,0]
	v_exp_f32_e32 v57, v57
	v_exp_f32_e32 v59, v59
	v_exp_f32_e32 v50, v50
	v_exp_f32_e32 v51, v51
	v_exp_f32_e32 v48, v48
	v_exp_f32_e32 v49, v49
	v_pk_add_f32 v[56:57], v[56:57], 1.0 op_sel_hi:[1,0]
	v_pk_add_f32 v[58:59], v[58:59], 1.0 op_sel_hi:[1,0]
	v_pk_add_f32 v[50:51], v[50:51], 1.0 op_sel_hi:[1,0]
	v_pk_add_f32 v[48:49], v[48:49], 1.0 op_sel_hi:[1,0]
	v_rcp_f32_e32 v58, v58
	v_rcp_f32_e32 v59, v59
	v_rcp_f32_e32 v56, v56
	v_rcp_f32_e32 v57, v57
	v_rcp_f32_e32 v50, v50
	v_rcp_f32_e32 v51, v51
	v_rcp_f32_e32 v48, v48
	v_rcp_f32_e32 v49, v49
	v_pk_mul_f32 v[34:35], v[42:43], v[34:35]
	v_pk_mul_f32 v[32:33], v[40:41], v[32:33]
	v_pk_mul_f32 v[38:39], v[46:47], v[38:39]
	v_pk_mul_f32 v[36:37], v[44:45], v[36:37]
	v_pk_mul_f32 v[40:41], v[56:57], v[34:35]
	v_pk_mul_f32 v[34:35], v[58:59], v[32:33]
	v_pk_mul_f32 v[38:39], v[48:49], v[38:39]
	v_pk_mul_f32 v[36:37], v[50:51], v[36:37]
	v_pk_mul_f32 v[22:23], v[30:31], v[22:23]
	v_cvt_pk_bf16_f32 v32, v36, v37
	v_cvt_pk_bf16_f32 v33, v38, v39
	v_cvt_pk_bf16_f32 v34, v34, v35
	v_cvt_pk_bf16_f32 v35, v40, v41
	global_store_dwordx4 v[52:53], v[32:35], off offset:2048 nt
	v_pk_mul_f32 v[36:37], v[26:27], s[12:13] op_sel_hi:[1,0]
	v_pk_mul_f32 v[38:39], v[24:25], s[12:13] op_sel_hi:[1,0]
	v_pk_mul_f32 v[32:33], v[30:31], s[12:13] op_sel_hi:[1,0]
	v_pk_mul_f32 v[34:35], v[28:29], s[12:13] op_sel_hi:[1,0]
	v_exp_f32_e32 v38, v38
	v_exp_f32_e32 v34, v34
	v_exp_f32_e32 v35, v35
	v_exp_f32_e32 v32, v32
	v_exp_f32_e32 v33, v33
	v_exp_f32_e32 v36, v36
	v_exp_f32_e32 v37, v37
	v_exp_f32_e32 v39, v39
	v_pk_add_f32 v[32:33], v[32:33], 1.0 op_sel_hi:[1,0]
	v_pk_add_f32 v[34:35], v[34:35], 1.0 op_sel_hi:[1,0]
	v_pk_add_f32 v[36:37], v[36:37], 1.0 op_sel_hi:[1,0]
	v_pk_add_f32 v[38:39], v[38:39], 1.0 op_sel_hi:[1,0]
	v_rcp_f32_e32 v34, v34
	v_rcp_f32_e32 v38, v38
	v_rcp_f32_e32 v35, v35
	v_rcp_f32_e32 v39, v39
	v_rcp_f32_e32 v32, v32
	v_rcp_f32_e32 v36, v36
	v_rcp_f32_e32 v33, v33
	v_rcp_f32_e32 v37, v37
	v_pk_mul_f32 v[20:21], v[28:29], v[20:21]
	v_pk_mul_f32 v[18:19], v[26:27], v[18:19]
	v_pk_mul_f32 v[16:17], v[24:25], v[16:17]
	v_pk_mul_f32 v[22:23], v[32:33], v[22:23]
	v_pk_mul_f32 v[20:21], v[34:35], v[20:21]
	v_pk_mul_f32 v[24:25], v[36:37], v[18:19]
	v_pk_mul_f32 v[18:19], v[38:39], v[16:17]
	v_cvt_pk_bf16_f32 v16, v20, v21
	v_cvt_pk_bf16_f32 v17, v22, v23
	v_pk_mul_f32 v[20:21], v[10:11], s[12:13] op_sel_hi:[1,0]
	v_cvt_pk_bf16_f32 v18, v18, v19
	v_cvt_pk_bf16_f32 v19, v24, v25
	v_pk_mul_f32 v[22:23], v[8:9], s[12:13] op_sel_hi:[1,0]
	global_store_dwordx4 v[54:55], v[16:19], off nt
	v_exp_f32_e32 v22, v22
	v_exp_f32_e32 v20, v20
	v_pk_mul_f32 v[16:17], v[14:15], s[12:13] op_sel_hi:[1,0]
	v_pk_mul_f32 v[18:19], v[12:13], s[12:13] op_sel_hi:[1,0]
	v_exp_f32_e32 v21, v21
	v_exp_f32_e32 v23, v23
	v_exp_f32_e32 v18, v18
	v_exp_f32_e32 v19, v19
	v_exp_f32_e32 v16, v16
	v_exp_f32_e32 v17, v17
	v_pk_add_f32 v[20:21], v[20:21], 1.0 op_sel_hi:[1,0]
	v_pk_add_f32 v[22:23], v[22:23], 1.0 op_sel_hi:[1,0]
	v_pk_add_f32 v[18:19], v[18:19], 1.0 op_sel_hi:[1,0]
	v_pk_add_f32 v[16:17], v[16:17], 1.0 op_sel_hi:[1,0]
	v_rcp_f32_e32 v22, v22
	v_rcp_f32_e32 v23, v23
	v_rcp_f32_e32 v20, v20
	v_rcp_f32_e32 v21, v21
	v_rcp_f32_e32 v18, v18
	v_rcp_f32_e32 v19, v19
	v_rcp_f32_e32 v16, v16
	v_rcp_f32_e32 v17, v17
	v_pk_mul_f32 v[2:3], v[10:11], v[2:3]
	v_pk_mul_f32 v[0:1], v[8:9], v[0:1]
	v_pk_mul_f32 v[6:7], v[14:15], v[6:7]
	v_pk_mul_f32 v[4:5], v[12:13], v[4:5]
	v_pk_mul_f32 v[8:9], v[20:21], v[2:3]
	v_pk_mul_f32 v[2:3], v[22:23], v[0:1]
	s_andn2_b64 vcc, exec, s[0:1]
	s_mov_b64 s[0:1], -1
	v_pk_mul_f32 v[6:7], v[16:17], v[6:7]
	v_pk_mul_f32 v[4:5], v[18:19], v[4:5]
	s_nop 0
	v_cvt_pk_bf16_f32 v0, v4, v5
	v_cvt_pk_bf16_f32 v1, v6, v7
	v_cvt_pk_bf16_f32 v2, v2, v3
	v_cvt_pk_bf16_f32 v3, v8, v9
	global_store_dwordx4 v[54:55], v[0:3], off offset:2048 nt
	s_cbranch_vccnz .LBB0_2884
	s_andn2_b64 vcc, exec, s[8:9]
	s_cbranch_vccnz .LBB0_2883
	s_barrier
	s_branch .LBB0_2883
